# engine-1 only: K/V stage loads via SGPR base + 32-bit lane offsets
# baseline (speedup 1.0000x reference)
.LBB0_578:
	s_andn2_b64 vcc, exec, s[18:19]
	s_cbranch_vccnz .LBB0_513
	s_ashr_i32 s0, s28, 5
	s_lshl_b32 s2, s28, 7
	s_lshl_b32 s1, s0, 12
	s_and_b32 s2, s2, 0xf80
	s_or_b32 s20, s1, s2
	s_ashr_i32 s21, s20, 31
	s_lshl_b64 s[18:19], s[20:21], 14
	s_add_u32 s2, s4, s18
	s_addc_u32 s19, s5, s19
	s_lshl_b32 s18, s80, 1
	s_add_u32 s2, s2, s18
	v_mov_b32_e32 v200, v175
	s_addc_u32 s19, s19, 0
	s_waitcnt vmcnt(2)
	v_mov_b32_e32 v44, v175
	global_load_dword v176, v1, s[8:9]
	global_load_dword v201, v1, s[8:9] offset:8
	s_add_u32 s24, s2, 0x1000
	s_addc_u32 s25, s19, 0
	v_ashrrev_i32_e32 v161, 3, v44
	s_lshl_b32 s2, s0, 10
	v_add_u32_e32 v4, s1, v161
	s_or_b32 s2, s2, s80
	v_and_b32_e32 v0, 48, v44
	v_ashrrev_i32_e32 v5, 31, v4
	s_mul_hi_i32 s19, s2, 0x2200
	s_mulk_i32 s2, 0x2200
	v_lshl_add_u64 v[2:3], s[24:25], 0, v[0:1]
	v_lshlrev_b64 v[4:5], 14, v[4:5]
	v_lshlrev_b32_e32 v0, 4, v44
	s_add_u32 s22, s35, s2
	v_lshl_add_u64 v[4:5], s[14:15], 0, v[4:5]
	v_and_b32_e32 v0, 0x70, v0
	s_addc_u32 s23, s36, s19
	v_lshl_add_u64 v[4:5], v[4:5], 0, v[0:1]
	v_add_co_u32_e32 v6, vcc, s61, v4
	v_lshl_add_u64 v[140:141], s[22:23], 0, v[0:1]
	s_nop 0
	v_addc_co_u32_e32 v7, vcc, 0, v5, vcc
	global_load_dwordx4 v[20:23], v[4:5], off
	global_load_dwordx4 v[24:27], v[6:7], off
	v_mad_i64_i32 v[4:5], s[26:27], v161, s74, v[140:141]
	v_add_u32_e32 v45, 32, v161
	v_add_u32_e32 v46, 64, v161
	v_mad_i64_i32 v[6:7], s[26:27], v45, s74, v[140:141]
	global_load_dwordx4 v[28:31], v[4:5], off
	global_load_dwordx4 v[32:35], v[6:7], off
	v_mad_i64_i32 v[4:5], s[26:27], v46, s74, v[140:141]
	v_add_u32_e32 v47, 0x60, v161
	v_mad_i64_i32 v[6:7], s[26:27], v47, s74, v[140:141]
	global_load_dwordx4 v[36:39], v[4:5], off
	global_load_dwordx4 v[40:43], v[6:7], off
	v_and_b32_e32 v48, 15, v44
	v_ashrrev_i32_e32 v4, 1, v44
	v_and_or_b32 v8, v4, s96, v48
	v_ashrrev_i32_e32 v9, 31, v8
	v_lshlrev_b64 v[4:5], 14, v[8:9]
	v_or_b32_e32 v8, 16, v8
	v_ashrrev_i32_e32 v9, 31, v8
	v_lshlrev_b64 v[8:9], 14, v[8:9]
	v_lshl_add_u64 v[4:5], v[2:3], 0, v[4:5]
	v_lshl_add_u64 v[2:3], v[2:3], 0, v[8:9]
	global_load_dwordx4 v[12:15], v[4:5], off
	s_nop 0
	global_load_dwordx4 v[4:7], v[4:5], off offset:64
	s_nop 0
	global_load_dwordx4 v[16:19], v[2:3], off
	global_load_dwordx4 v[8:11], v[2:3], off offset:64
	v_lshrrev_b32_e32 v49, 1, v161
	v_xor_b32_e32 v49, v49, v44
	v_mad_i64_i32 v[144:145], s[26:27], v45, s74, 0
	v_lshlrev_b32_e32 v45, 4, v49
	v_lshlrev_b32_e32 v162, 7, v161
	v_and_b32_e32 v163, 0x70, v45
	v_or_b32_e32 v164, v163, v162
	v_and_b32_e32 v2, 63, v44
	v_bfe_u32 v3, v44, 4, 2
	v_add_u32_e32 v45, 0, v164
	v_lshl_add_u64 v[150:151], s[14:15], 0, v[0:1]
	v_lshrrev_b32_e32 v0, 1, v44
	v_lshlrev_b32_e32 v2, 2, v2
	v_bitop3_b32 v0, v3, v0, 7 bitop3:0x78
	v_xor_b32_e32 v156, 0x80, v2
	v_lshlrev_b32_e32 v159, 4, v0
	v_mov_b32_e32 v2, v1
	v_mad_i64_i32 v[146:147], s[26:27], v46, s74, 0
	v_mad_i64_i32 v[148:149], s[26:27], v47, s74, 0
	s_lshl_b32 s2, s0, 8
	v_lshlrev_b32_e32 v160, 7, v48
	v_mov_b32_e32 v179, v178
	s_mov_b32 s19, 0
	v_mad_i64_i32 v[142:143], s[26:27], v161, s74, 0
	s_addk_i32 s2, 0x3040
	v_mov_b32_e32 v158, 0
	s_mov_b32 s0, 0
	v_mov_b64_e32 v[152:153], v[178:179]
	s_waitcnt vmcnt(9)
	ds_write_b128 v45, v[20:23]
	s_waitcnt vmcnt(8)
	ds_write_b128 v45, v[24:27] offset:4096
	s_waitcnt vmcnt(7)
	ds_write_b128 v45, v[28:31] offset:8192
	s_waitcnt vmcnt(6)
	ds_write_b128 v45, v[32:35] offset:12288
	s_waitcnt vmcnt(5)
	ds_write_b128 v45, v[36:39] offset:16384
	s_waitcnt vmcnt(4)
	ds_write_b128 v45, v[40:43] offset:20480
	v_bfe_u32 v20, v44, 1, 3
	v_bitop3_b32 v0, v3, v20, 4 bitop3:0x36
	v_mov_b32_e32 v3, v1
	v_lshlrev_b32_e32 v157, 4, v0
	v_mov_b32_e32 v0, v1
	v_mov_b64_e32 v[22:23], v[2:3]
	v_mov_b64_e32 v[30:31], v[2:3]
	v_mov_b64_e32 v[26:27], v[2:3]
	v_mov_b64_e32 v[38:39], v[2:3]
	v_mov_b64_e32 v[34:35], v[2:3]
	v_mov_b64_e32 v[42:43], v[2:3]
	v_mov_b64_e32 v[46:47], v[2:3]
	v_mov_b64_e32 v[50:51], v[2:3]
	v_mov_b64_e32 v[54:55], v[2:3]
	v_mov_b64_e32 v[58:59], v[2:3]
	v_mov_b64_e32 v[62:63], v[2:3]
	v_mov_b64_e32 v[66:67], v[2:3]
	v_mov_b64_e32 v[70:71], v[2:3]
	v_mov_b64_e32 v[74:75], v[2:3]
	v_mov_b64_e32 v[78:79], v[2:3]
	v_mov_b64_e32 v[82:83], v[2:3]
	v_mov_b64_e32 v[20:21], v[0:1]
	v_mov_b64_e32 v[28:29], v[0:1]
	v_mov_b64_e32 v[24:25], v[0:1]
	v_mov_b64_e32 v[36:37], v[0:1]
	v_mov_b64_e32 v[32:33], v[0:1]
	v_mov_b64_e32 v[40:41], v[0:1]
	v_mov_b64_e32 v[44:45], v[0:1]
	v_mov_b64_e32 v[48:49], v[0:1]
	v_mov_b64_e32 v[52:53], v[0:1]
	v_mov_b64_e32 v[56:57], v[0:1]
	v_mov_b64_e32 v[60:61], v[0:1]
	v_mov_b64_e32 v[64:65], v[0:1]
	v_mov_b64_e32 v[68:69], v[0:1]
	v_mov_b64_e32 v[72:73], v[0:1]
	v_mov_b64_e32 v[76:77], v[0:1]
	v_mov_b64_e32 v[80:81], v[0:1]
	v_mov_b32_e32 v0, 0
	v_subrev_u32_e32 v141, s14, v150
	v_lshl_add_u32 v150, v161, 14, v141
	v_add_u32_e32 v151, 0x80000, v150
	v_add_u32_e32 v142, v142, v141
	v_add_u32_e32 v144, v144, v141
	v_add_u32_e32 v146, v146, v141
	v_add_u32_e32 v148, v148, v141

.LBB0_584:
	s_bitcmp1_b32 s0, 0
	s_cselect_b32 s0, 0x6000, 0
	s_add_i32 s28, s0, 0
	s_add_i32 s19, s19, 64
	s_add_i32 s0, s42, 0x1000
	s_and_b64 s[26:27], s[26:27], exec
	s_cselect_b32 s42, s19, s0
	s_lshl_b32 s100, s44, 14
	s_add_u32 s100, s14, s100
	s_addc_u32 s101, s15, 0
	global_load_dwordx4 v[84:87], v150, s[100:101]
	global_load_dwordx4 v[88:91], v151, s[100:101]
	s_lshl_b32 s100, s42, 1
	s_add_u32 s100, s22, s100
	s_addc_u32 s101, s23, 0
	global_load_dwordx4 v[92:95], v142, s[100:101]
	global_load_dwordx4 v[104:107], v148, s[100:101]
	v_add3_u32 v2, s28, v159, v160
	global_load_dwordx4 v[96:99], v144, s[100:101]
	ds_read_b128 v[108:111], v2
	ds_read_b128 v[116:119], v2 offset:2048
	global_load_dwordx4 v[100:103], v146, s[100:101]
	v_add3_u32 v3, s28, v157, v160
	ds_read_b128 v[124:127], v3
	ds_read_b128 v[170:173], v3 offset:4096
	s_waitcnt vmcnt(9) lgkmcnt(3)
	v_mfma_f32_16x16x32_bf16 v[112:115], v[108:111], v[12:15], 0
	s_waitcnt vmcnt(7)
	v_mfma_f32_16x16x32_bf16 v[108:111], v[108:111], v[16:19], 0
	s_waitcnt lgkmcnt(1)
	v_mfma_f32_16x16x32_bf16 v[136:139], v[124:127], v[4:7], v[112:115]
	s_waitcnt vmcnt(6)
	v_mfma_f32_16x16x32_bf16 v[124:127], v[124:127], v[8:11], v[108:111]
	s_nop 3
	ds_read_b128 v[108:111], v3 offset:2048
	v_mfma_f32_16x16x32_bf16 v[120:123], v[116:119], v[12:15], 0
	v_mfma_f32_16x16x32_bf16 v[116:119], v[116:119], v[16:19], 0
	s_waitcnt lgkmcnt(0)
	v_mfma_f32_16x16x32_bf16 v[132:135], v[108:111], v[4:7], v[120:123]
	v_mfma_f32_16x16x32_bf16 v[128:131], v[108:111], v[8:11], v[116:119]
	ds_read_b128 v[108:111], v2 offset:4096
	s_nop 3
	ds_read_b128 v[116:119], v2 offset:6144
	s_waitcnt lgkmcnt(1)
	v_mfma_f32_16x16x32_bf16 v[112:115], v[108:111], v[12:15], 0
	v_max3_f32 v2, v136, v137, v138
	s_nop 0
	v_max3_f32 v2, v2, v139, v132
	s_waitcnt lgkmcnt(0)
	v_mfma_f32_16x16x32_bf16 v[120:123], v[116:119], v[12:15], 0
	v_max3_f32 v2, v2, v133, v134
	s_nop 0
	v_max3_f32 v2, v2, v135, v135
	v_mfma_f32_16x16x32_bf16 v[166:169], v[116:119], v[16:19], 0
	v_mul_f32_e32 v2, 0x3e38aa3b, v2
	v_mfma_f32_16x16x32_bf16 v[116:119], v[170:173], v[4:7], v[112:115]
	s_nop 2
	ds_read_b128 v[112:115], v3 offset:6144
	v_mfma_f32_16x16x32_bf16 v[108:111], v[108:111], v[16:19], 0
	v_add_f32_e32 v3, 0x41000000, v152
	v_cmp_gt_f32_e32 vcc, v2, v3
	v_mfma_f32_16x16x32_bf16 v[108:111], v[170:173], v[8:11], v[108:111]
	s_waitcnt lgkmcnt(0)
	v_mfma_f32_16x16x32_bf16 v[120:123], v[112:115], v[4:7], v[120:123]
	v_mfma_f32_16x16x32_bf16 v[112:115], v[112:115], v[8:11], v[166:169]
	s_cbranch_vccz .LBB0_586
	ds_swizzle_b32 v3, v2 offset:swizzle(SWAP,16)
	v_max_f32_e32 v2, v2, v2
	s_waitcnt lgkmcnt(0)
	v_max_f32_e32 v3, v3, v3
	v_max_f32_e32 v2, v2, v3
	ds_bpermute_b32 v3, v156, v2
	s_waitcnt lgkmcnt(0)
	v_max3_f32 v2, v152, v2, v3
	v_sub_f32_e32 v3, v152, v2
	v_exp_f32_e32 v152, v3
	v_mov_b32_e32 v3, v153
	v_mul_f32_e32 v0, v0, v152
	v_pk_mul_f32 v[82:83], v[82:83], v[152:153] op_sel_hi:[1,0]
	v_pk_mul_f32 v[80:81], v[80:81], v[152:153] op_sel_hi:[1,0]
	v_pk_mul_f32 v[74:75], v[74:75], v[152:153] op_sel_hi:[1,0]
	v_pk_mul_f32 v[72:73], v[72:73], v[152:153] op_sel_hi:[1,0]
	v_pk_mul_f32 v[66:67], v[66:67], v[152:153] op_sel_hi:[1,0]
	v_pk_mul_f32 v[64:65], v[64:65], v[152:153] op_sel_hi:[1,0]
	v_pk_mul_f32 v[58:59], v[58:59], v[152:153] op_sel_hi:[1,0]
	v_pk_mul_f32 v[56:57], v[56:57], v[152:153] op_sel_hi:[1,0]
	v_pk_mul_f32 v[50:51], v[50:51], v[152:153] op_sel_hi:[1,0]
	v_pk_mul_f32 v[48:49], v[48:49], v[152:153] op_sel_hi:[1,0]
	v_pk_mul_f32 v[42:43], v[42:43], v[152:153] op_sel_hi:[1,0]
	v_pk_mul_f32 v[40:41], v[40:41], v[152:153] op_sel_hi:[1,0]
	v_pk_mul_f32 v[38:39], v[38:39], v[152:153] op_sel_hi:[1,0]
	v_pk_mul_f32 v[36:37], v[36:37], v[152:153] op_sel_hi:[1,0]
	v_pk_mul_f32 v[30:31], v[30:31], v[152:153] op_sel_hi:[1,0]
	v_pk_mul_f32 v[28:29], v[28:29], v[152:153] op_sel_hi:[1,0]
	v_mov_b32_e32 v152, v2
	s_branch .LBB0_587
